# P5: L2 touch prefetch of the residual x tile one K iteration before the full tile's epilogue (dword touches, results discarded)
# speedup vs baseline: 1.0034x; 1.0034x over previous
.LBB0_1259:
	ds_read_b128 v[130:133], v182
	ds_read_b128 v[134:137], v182 offset:1024
	ds_read_b128 v[138:141], v182 offset:2048
	ds_read_b128 v[142:145], v182 offset:3072
	ds_read_b128 v[146:149], v183
	ds_read_b128 v[150:153], v183 offset:1024
	ds_read_b128 v[154:157], v183 offset:2048
	ds_read_b128 v[158:161], v183 offset:3072
	s_add_i32 s51, s50, 2
	s_add_u32 s59, s10, 0xfffc0080
	s_addc_u32 s61, s11, -1
	s_cmp_eq_u32 s45, s50
	s_cselect_b32 s75, s39, s61
	s_cselect_b32 s74, s42, s59
	s_cselect_b32 s73, s43, s49
	s_cselect_b32 s72, s44, s48
	v_lshl_add_u64 v[210:211], s[10:11], 0, v[168:169]
	s_add_i32 m0, s5, 0xc000
	ds_read_b128 v[172:175], v184
	ds_read_b128 v[176:179], v184 offset:1024
	ds_read_b128 v[186:189], v184 offset:2048
	ds_read_b128 v[190:193], v184 offset:3072
	ds_read_b128 v[194:197], v184 offset:4096
	ds_read_b128 v[198:201], v184 offset:5120
	ds_read_b128 v[202:205], v184 offset:6144
	ds_read_b128 v[206:209], v184 offset:7168
	global_load_lds_dwordx4 v[210:211], off
	v_lshl_add_u64 v[210:211], s[10:11], 0, v[170:171]
	s_add_i32 m0, s5, 0xe000
	s_nop 0
	global_load_lds_dwordx4 v[210:211], off
	s_waitcnt vmcnt(8)
	s_waitcnt lgkmcnt(0)
	s_barrier
	s_setprio 1
	s_waitcnt lgkmcnt(0)
	v_mfma_f32_16x16x32_bf16 v[126:129], v[130:133], v[172:175], v[126:129]
	v_mfma_f32_16x16x32_bf16 v[122:125], v[138:141], v[172:175], v[122:125]
	v_mfma_f32_16x16x32_bf16 v[110:113], v[130:133], v[186:189], v[110:113]
	v_mfma_f32_16x16x32_bf16 v[106:109], v[138:141], v[186:189], v[106:109]
	v_mfma_f32_16x16x32_bf16 v[94:97], v[130:133], v[194:197], v[94:97]
	v_mfma_f32_16x16x32_bf16 v[90:93], v[138:141], v[194:197], v[90:93]
	v_mfma_f32_16x16x32_bf16 v[78:81], v[130:133], v[202:205], v[78:81]
	v_mfma_f32_16x16x32_bf16 v[74:77], v[138:141], v[202:205], v[74:77]
	v_mfma_f32_16x16x32_bf16 v[126:129], v[134:137], v[176:179], v[126:129]
	v_mfma_f32_16x16x32_bf16 v[122:125], v[142:145], v[176:179], v[122:125]
	v_mfma_f32_16x16x32_bf16 v[110:113], v[134:137], v[190:193], v[110:113]
	v_mfma_f32_16x16x32_bf16 v[106:109], v[142:145], v[190:193], v[106:109]
	v_mfma_f32_16x16x32_bf16 v[94:97], v[134:137], v[198:201], v[94:97]
	v_mfma_f32_16x16x32_bf16 v[90:93], v[142:145], v[198:201], v[90:93]
	v_mfma_f32_16x16x32_bf16 v[78:81], v[134:137], v[206:209], v[78:81]
	v_mfma_f32_16x16x32_bf16 v[74:77], v[142:145], v[206:209], v[74:77]
	s_setprio 0
	s_setprio 1
	v_mfma_f32_16x16x32_bf16 v[118:121], v[146:149], v[172:175], v[118:121]
	v_mfma_f32_16x16x32_bf16 v[114:117], v[154:157], v[172:175], v[114:117]
	v_mfma_f32_16x16x32_bf16 v[102:105], v[146:149], v[186:189], v[102:105]
	v_mfma_f32_16x16x32_bf16 v[98:101], v[154:157], v[186:189], v[98:101]
	v_mfma_f32_16x16x32_bf16 v[86:89], v[146:149], v[194:197], v[86:89]
	v_mfma_f32_16x16x32_bf16 v[82:85], v[154:157], v[194:197], v[82:85]
	v_mfma_f32_16x16x32_bf16 v[70:73], v[146:149], v[202:205], v[70:73]
	v_mfma_f32_16x16x32_bf16 v[66:69], v[154:157], v[202:205], v[66:69]
	v_mfma_f32_16x16x32_bf16 v[118:121], v[150:153], v[176:179], v[118:121]
	v_mfma_f32_16x16x32_bf16 v[114:117], v[158:161], v[176:179], v[114:117]
	v_mfma_f32_16x16x32_bf16 v[102:105], v[150:153], v[190:193], v[102:105]
	v_mfma_f32_16x16x32_bf16 v[98:101], v[158:161], v[190:193], v[98:101]
	v_mfma_f32_16x16x32_bf16 v[86:89], v[150:153], v[198:201], v[86:89]
	v_mfma_f32_16x16x32_bf16 v[82:85], v[158:161], v[198:201], v[82:85]
	v_mfma_f32_16x16x32_bf16 v[70:73], v[150:153], v[206:209], v[70:73]
	v_mfma_f32_16x16x32_bf16 v[66:69], v[158:161], v[206:209], v[66:69]
	s_setprio 0
	s_barrier
	s_add_i32 s50, s68, s4
	v_lshl_add_u64 v[210:211], s[72:73], 0, v[162:163]
	s_mov_b32 m0, s50
	ds_read_b128 v[172:175], v184 offset:16384
	ds_read_b128 v[176:179], v184 offset:17408
	ds_read_b128 v[186:189], v184 offset:18432
	ds_read_b128 v[190:193], v184 offset:19456
	ds_read_b128 v[194:197], v184 offset:20480
	ds_read_b128 v[198:201], v184 offset:21504
	ds_read_b128 v[202:205], v184 offset:22528
	ds_read_b128 v[206:209], v184 offset:23552
	global_load_lds_dwordx4 v[210:211], off
	s_add_i32 m0, s50, 0x2000
	s_add_u32 s80, s72, 0x40000
	v_lshl_add_u64 v[212:213], s[72:73], 0, v[164:165]
	s_addc_u32 s81, s73, 0
	s_add_i32 s50, s69, s4
	global_load_lds_dwordx4 v[212:213], off
	v_lshl_add_u64 v[214:215], s[80:81], 0, v[162:163]
	s_mov_b32 m0, s50
	v_lshl_add_u64 v[216:217], s[74:75], 0, v[164:165]
	global_load_lds_dwordx4 v[214:215], off
	v_lshl_add_u64 v[214:215], s[80:81], 0, v[164:165]
	s_add_i32 m0, s50, 0x2000
	s_nop 0
	global_load_lds_dwordx4 v[214:215], off
	v_lshl_add_u64 v[214:215], s[74:75], 0, v[162:163]
	s_mov_b32 m0, s5
	s_nop 0
	global_load_lds_dwordx4 v[214:215], off
	s_mov_b32 m0, s27
	s_nop 0
	global_load_lds_dwordx4 v[216:217], off
	s_waitcnt vmcnt(8)
	s_waitcnt lgkmcnt(0)
	s_barrier
	s_setprio 1
	s_waitcnt lgkmcnt(0)
	v_mfma_f32_16x16x32_bf16 v[62:65], v[130:133], v[172:175], v[62:65]
	v_mfma_f32_16x16x32_bf16 v[58:61], v[138:141], v[172:175], v[58:61]
	v_mfma_f32_16x16x32_bf16 v[46:49], v[130:133], v[186:189], v[46:49]
	v_mfma_f32_16x16x32_bf16 v[42:45], v[138:141], v[186:189], v[42:45]
	v_mfma_f32_16x16x32_bf16 v[30:33], v[130:133], v[194:197], v[30:33]
	v_mfma_f32_16x16x32_bf16 v[26:29], v[138:141], v[194:197], v[26:29]
	v_mfma_f32_16x16x32_bf16 v[14:17], v[130:133], v[202:205], v[14:17]
	v_mfma_f32_16x16x32_bf16 v[10:13], v[138:141], v[202:205], v[10:13]
	v_mfma_f32_16x16x32_bf16 v[62:65], v[134:137], v[176:179], v[62:65]
	v_mfma_f32_16x16x32_bf16 v[58:61], v[142:145], v[176:179], v[58:61]
	v_mfma_f32_16x16x32_bf16 v[46:49], v[134:137], v[190:193], v[46:49]
	v_mfma_f32_16x16x32_bf16 v[42:45], v[142:145], v[190:193], v[42:45]
	v_mfma_f32_16x16x32_bf16 v[30:33], v[134:137], v[198:201], v[30:33]
	v_mfma_f32_16x16x32_bf16 v[26:29], v[142:145], v[198:201], v[26:29]
	v_mfma_f32_16x16x32_bf16 v[14:17], v[134:137], v[206:209], v[14:17]
	v_mfma_f32_16x16x32_bf16 v[10:13], v[142:145], v[206:209], v[10:13]
	s_setprio 0
	s_setprio 1
	v_mfma_f32_16x16x32_bf16 v[54:57], v[146:149], v[172:175], v[54:57]
	v_mfma_f32_16x16x32_bf16 v[50:53], v[154:157], v[172:175], v[50:53]
	v_mfma_f32_16x16x32_bf16 v[38:41], v[146:149], v[186:189], v[38:41]
	v_mfma_f32_16x16x32_bf16 v[34:37], v[154:157], v[186:189], v[34:37]
	v_mfma_f32_16x16x32_bf16 v[22:25], v[146:149], v[194:197], v[22:25]
	v_mfma_f32_16x16x32_bf16 v[18:21], v[154:157], v[194:197], v[18:21]
	v_mfma_f32_16x16x32_bf16 v[6:9], v[146:149], v[202:205], v[6:9]
	v_mfma_f32_16x16x32_bf16 v[2:5], v[154:157], v[202:205], v[2:5]
	v_mfma_f32_16x16x32_bf16 v[54:57], v[150:153], v[176:179], v[54:57]
	v_mfma_f32_16x16x32_bf16 v[50:53], v[158:161], v[176:179], v[50:53]
	v_mfma_f32_16x16x32_bf16 v[38:41], v[150:153], v[190:193], v[38:41]
	v_mfma_f32_16x16x32_bf16 v[34:37], v[158:161], v[190:193], v[34:37]
	v_mfma_f32_16x16x32_bf16 v[22:25], v[150:153], v[198:201], v[22:25]
	v_mfma_f32_16x16x32_bf16 v[18:21], v[158:161], v[198:201], v[18:21]
	v_mfma_f32_16x16x32_bf16 v[6:9], v[150:153], v[206:209], v[6:9]
	v_mfma_f32_16x16x32_bf16 v[2:5], v[158:161], v[206:209], v[2:5]
	s_setprio 0
	s_barrier
	s_add_i32 s50, 0, 0x18000
	s_add_i32 s59, 0, 0x1c000
	v_add_u32_e32 v142, s50, v180
	v_add_u32_e32 v158, s59, v180
	ds_read_b128 v[130:133], v142
	ds_read_b128 v[134:137], v142 offset:1024
	ds_read_b128 v[138:141], v142 offset:2048
	ds_read_b128 v[142:145], v142 offset:3072
	ds_read_b128 v[146:149], v158
	ds_read_b128 v[150:153], v158 offset:1024
	ds_read_b128 v[154:157], v158 offset:2048
	ds_read_b128 v[158:161], v158 offset:3072
	s_add_u32 s74, s74, 0x40000
	s_addc_u32 s75, s75, 0
	s_mov_b32 m0, s33
	v_lshl_add_u64 v[218:219], s[74:75], 0, v[162:163]
	ds_read_b128 v[172:175], v184 offset:32768
	ds_read_b128 v[176:179], v184 offset:33792
	ds_read_b128 v[186:189], v184 offset:34816
	ds_read_b128 v[190:193], v184 offset:35840
	ds_read_b128 v[194:197], v184 offset:36864
	ds_read_b128 v[198:201], v184 offset:37888
	ds_read_b128 v[202:205], v184 offset:38912
	ds_read_b128 v[206:209], v184 offset:39936
	global_load_lds_dwordx4 v[218:219], off
	v_lshl_add_u64 v[218:219], s[74:75], 0, v[164:165]
	s_mov_b32 m0, s52
	s_nop 0
	global_load_lds_dwordx4 v[218:219], off
	s_waitcnt vmcnt(8)
	s_waitcnt lgkmcnt(0)
	s_barrier
	s_setprio 1
	s_waitcnt lgkmcnt(0)
	v_mfma_f32_16x16x32_bf16 v[126:129], v[130:133], v[172:175], v[126:129]
	v_mfma_f32_16x16x32_bf16 v[122:125], v[138:141], v[172:175], v[122:125]
	v_mfma_f32_16x16x32_bf16 v[110:113], v[130:133], v[186:189], v[110:113]
	v_mfma_f32_16x16x32_bf16 v[106:109], v[138:141], v[186:189], v[106:109]
	v_mfma_f32_16x16x32_bf16 v[94:97], v[130:133], v[194:197], v[94:97]
	v_mfma_f32_16x16x32_bf16 v[90:93], v[138:141], v[194:197], v[90:93]
	v_mfma_f32_16x16x32_bf16 v[78:81], v[130:133], v[202:205], v[78:81]
	v_mfma_f32_16x16x32_bf16 v[74:77], v[138:141], v[202:205], v[74:77]
	v_mfma_f32_16x16x32_bf16 v[126:129], v[134:137], v[176:179], v[126:129]
	v_mfma_f32_16x16x32_bf16 v[122:125], v[142:145], v[176:179], v[122:125]
	v_mfma_f32_16x16x32_bf16 v[110:113], v[134:137], v[190:193], v[110:113]
	v_mfma_f32_16x16x32_bf16 v[106:109], v[142:145], v[190:193], v[106:109]
	v_mfma_f32_16x16x32_bf16 v[94:97], v[134:137], v[198:201], v[94:97]
	v_mfma_f32_16x16x32_bf16 v[90:93], v[142:145], v[198:201], v[90:93]
	v_mfma_f32_16x16x32_bf16 v[78:81], v[134:137], v[206:209], v[78:81]
	v_mfma_f32_16x16x32_bf16 v[74:77], v[142:145], v[206:209], v[74:77]
	s_setprio 0
	s_setprio 1
	v_mfma_f32_16x16x32_bf16 v[118:121], v[146:149], v[172:175], v[118:121]
	v_mfma_f32_16x16x32_bf16 v[114:117], v[154:157], v[172:175], v[114:117]
	v_mfma_f32_16x16x32_bf16 v[102:105], v[146:149], v[186:189], v[102:105]
	v_mfma_f32_16x16x32_bf16 v[98:101], v[154:157], v[186:189], v[98:101]
	v_mfma_f32_16x16x32_bf16 v[86:89], v[146:149], v[194:197], v[86:89]
	v_mfma_f32_16x16x32_bf16 v[82:85], v[154:157], v[194:197], v[82:85]
	v_mfma_f32_16x16x32_bf16 v[70:73], v[146:149], v[202:205], v[70:73]
	v_mfma_f32_16x16x32_bf16 v[66:69], v[154:157], v[202:205], v[66:69]
	v_mfma_f32_16x16x32_bf16 v[118:121], v[150:153], v[176:179], v[118:121]
	v_mfma_f32_16x16x32_bf16 v[114:117], v[158:161], v[176:179], v[114:117]
	v_mfma_f32_16x16x32_bf16 v[102:105], v[150:153], v[190:193], v[102:105]
	v_mfma_f32_16x16x32_bf16 v[98:101], v[158:161], v[190:193], v[98:101]
	v_mfma_f32_16x16x32_bf16 v[86:89], v[150:153], v[198:201], v[86:89]
	v_mfma_f32_16x16x32_bf16 v[82:85], v[158:161], v[198:201], v[82:85]
	v_mfma_f32_16x16x32_bf16 v[70:73], v[150:153], v[206:209], v[70:73]
	v_mfma_f32_16x16x32_bf16 v[66:69], v[158:161], v[206:209], v[66:69]
	s_setprio 0
	s_barrier
	s_add_i32 s50, s50, s4
	v_lshl_add_u64 v[210:211], v[210:211], 0, s[28:29]
	s_mov_b32 m0, s50
	ds_read_b128 v[172:175], v184 offset:49152
	ds_read_b128 v[176:179], v184 offset:50176
	ds_read_b128 v[186:189], v184 offset:51200
	ds_read_b128 v[190:193], v184 offset:52224
	ds_read_b128 v[194:197], v184 offset:53248
	ds_read_b128 v[198:201], v184 offset:54272
	ds_read_b128 v[202:205], v184 offset:55296
	ds_read_b128 v[206:209], v184 offset:56320
	global_load_lds_dwordx4 v[210:211], off
	s_add_i32 m0, s50, 0x2000
	s_add_u32 s72, s72, 0x40080
	v_lshl_add_u64 v[210:211], v[212:213], 0, s[28:29]
	s_addc_u32 s73, s73, 0
	s_add_i32 s50, s59, s4
	global_load_lds_dwordx4 v[210:211], off
	v_lshl_add_u64 v[210:211], s[72:73], 0, v[162:163]
	s_mov_b32 m0, s50
	s_nop 0
	global_load_lds_dwordx4 v[210:211], off
	v_lshl_add_u64 v[210:211], s[72:73], 0, v[164:165]
	s_add_i32 m0, s50, 0x2000
	s_nop 0
	global_load_lds_dwordx4 v[210:211], off
	v_lshl_add_u64 v[210:211], v[214:215], 0, s[28:29]
	s_mov_b32 m0, s66
	s_nop 0
	global_load_lds_dwordx4 v[210:211], off
	v_lshl_add_u64 v[210:211], v[216:217], 0, s[28:29]
	s_mov_b32 m0, s67
	s_nop 0
	global_load_lds_dwordx4 v[210:211], off
	s_waitcnt vmcnt(8)
	s_waitcnt lgkmcnt(0)
	s_barrier
	s_setprio 1
	s_waitcnt lgkmcnt(0)
	v_mfma_f32_16x16x32_bf16 v[62:65], v[130:133], v[172:175], v[62:65]
	v_mfma_f32_16x16x32_bf16 v[58:61], v[138:141], v[172:175], v[58:61]
	v_mfma_f32_16x16x32_bf16 v[46:49], v[130:133], v[186:189], v[46:49]
	v_mfma_f32_16x16x32_bf16 v[42:45], v[138:141], v[186:189], v[42:45]
	v_mfma_f32_16x16x32_bf16 v[30:33], v[130:133], v[194:197], v[30:33]
	v_mfma_f32_16x16x32_bf16 v[26:29], v[138:141], v[194:197], v[26:29]
	v_mfma_f32_16x16x32_bf16 v[14:17], v[130:133], v[202:205], v[14:17]
	v_mfma_f32_16x16x32_bf16 v[10:13], v[138:141], v[202:205], v[10:13]
	v_mfma_f32_16x16x32_bf16 v[62:65], v[134:137], v[176:179], v[62:65]
	v_mfma_f32_16x16x32_bf16 v[58:61], v[142:145], v[176:179], v[58:61]
	v_mfma_f32_16x16x32_bf16 v[46:49], v[134:137], v[190:193], v[46:49]
	v_mfma_f32_16x16x32_bf16 v[42:45], v[142:145], v[190:193], v[42:45]
	v_mfma_f32_16x16x32_bf16 v[30:33], v[134:137], v[198:201], v[30:33]
	v_mfma_f32_16x16x32_bf16 v[26:29], v[142:145], v[198:201], v[26:29]
	v_mfma_f32_16x16x32_bf16 v[14:17], v[134:137], v[206:209], v[14:17]
	v_mfma_f32_16x16x32_bf16 v[10:13], v[142:145], v[206:209], v[10:13]
	s_setprio 0
	s_setprio 1
	v_mfma_f32_16x16x32_bf16 v[54:57], v[146:149], v[172:175], v[54:57]
	v_mfma_f32_16x16x32_bf16 v[50:53], v[154:157], v[172:175], v[50:53]
	v_mfma_f32_16x16x32_bf16 v[38:41], v[146:149], v[186:189], v[38:41]
	v_mfma_f32_16x16x32_bf16 v[34:37], v[154:157], v[186:189], v[34:37]
	v_mfma_f32_16x16x32_bf16 v[22:25], v[146:149], v[194:197], v[22:25]
	v_mfma_f32_16x16x32_bf16 v[18:21], v[154:157], v[194:197], v[18:21]
	v_mfma_f32_16x16x32_bf16 v[6:9], v[146:149], v[202:205], v[6:9]
	v_mfma_f32_16x16x32_bf16 v[2:5], v[154:157], v[202:205], v[2:5]
	v_mfma_f32_16x16x32_bf16 v[54:57], v[150:153], v[176:179], v[54:57]
	v_mfma_f32_16x16x32_bf16 v[50:53], v[158:161], v[176:179], v[50:53]
	v_mfma_f32_16x16x32_bf16 v[38:41], v[150:153], v[190:193], v[38:41]
	v_mfma_f32_16x16x32_bf16 v[34:37], v[158:161], v[190:193], v[34:37]
	v_mfma_f32_16x16x32_bf16 v[22:25], v[150:153], v[198:201], v[22:25]
	v_mfma_f32_16x16x32_bf16 v[18:21], v[158:161], v[198:201], v[18:21]
	v_mfma_f32_16x16x32_bf16 v[6:9], v[150:153], v[206:209], v[6:9]
	v_mfma_f32_16x16x32_bf16 v[2:5], v[158:161], v[206:209], v[2:5]
	s_setprio 0
	s_barrier
	s_cmp_lg_u32 s50, 12
	s_cbranch_scc1 .Lp5pf_skip
	v_lshl_add_u32 v230, s17, 8, v1
	v_readlane_b32 vcc_lo, v245, 0
	v_readlane_b32 vcc_hi, v245, 1
	s_cmp_gt_i32 s17, 63
	s_cbranch_scc0 .Lp5pf_b0
	v_readlane_b32 vcc_lo, v245, 2
	v_readlane_b32 vcc_hi, v245, 3
	v_add_u32_e32 v230, 0xffffc000, v230
.Lp5pf_b0:
	v_lshl_or_b32 v228, s26, 8, v181
	v_lshlrev_b32_e32 v228, 2, v228
	v_mov_b32_e32 v229, 0
	v_mov_b32_e32 v231, 0
	v_lshlrev_b64 v[230:231], 12, v[230:231]
	s_nop 1
	v_lshl_add_u64 v[230:231], vcc, 0, v[230:231]
	v_lshl_add_u64 v[230:231], v[230:231], 0, v[228:229]
	v_mov_b64_e32 v[232:233], v[230:231]
	global_load_dword v226, v[232:233], off
	global_load_dword v226, v[232:233], off offset:512
	v_add_co_u32_e32 v232, vcc, 0x10000, v232
	s_nop 1
	v_addc_co_u32_e32 v233, vcc, 0, v233, vcc
	global_load_dword v226, v[232:233], off
	global_load_dword v226, v[232:233], off offset:512
	v_add_co_u32_e32 v232, vcc, 0x10000, v232
	s_nop 1
	v_addc_co_u32_e32 v233, vcc, 0, v233, vcc
	global_load_dword v226, v[232:233], off
	global_load_dword v226, v[232:233], off offset:512
	v_add_co_u32_e32 v232, vcc, 0x10000, v232
	s_nop 1
	v_addc_co_u32_e32 v233, vcc, 0, v233, vcc
	global_load_dword v226, v[232:233], off
	global_load_dword v226, v[232:233], off offset:512
	v_mov_b64_e32 v[232:233], v[230:231]
	v_add_co_u32_e32 v232, vcc, 0x80000, v232
	s_nop 1
	v_addc_co_u32_e32 v233, vcc, 0, v233, vcc
	global_load_dword v226, v[232:233], off
	global_load_dword v226, v[232:233], off offset:512
	v_add_co_u32_e32 v232, vcc, 0x10000, v232
	s_nop 1
	v_addc_co_u32_e32 v233, vcc, 0, v233, vcc
	global_load_dword v226, v[232:233], off
	global_load_dword v226, v[232:233], off offset:512
	v_add_co_u32_e32 v232, vcc, 0x10000, v232
	s_nop 1
	v_addc_co_u32_e32 v233, vcc, 0, v233, vcc
	global_load_dword v226, v[232:233], off
	global_load_dword v226, v[232:233], off offset:512
	v_add_co_u32_e32 v232, vcc, 0x10000, v232
	s_nop 1
	v_addc_co_u32_e32 v233, vcc, 0, v233, vcc
	global_load_dword v226, v[232:233], off
	global_load_dword v226, v[232:233], off offset:512
.Lp5pf_skip:
	s_add_u32 s10, s10, 0x100
	s_addc_u32 s11, s11, 0
	s_add_u32 s48, s48, 0x100
	s_addc_u32 s49, s49, 0
	s_cmp_ge_u32 s51, s38
	s_mov_b32 s50, s51
	s_cbranch_scc0 .LBB0_1259
	s_and_b64 vcc, exec, s[30:31]
	s_cbranch_vccz .LBB0_1262
